# gated branch GEMM K-loop rewritten software-pipelined (A fragments double-buffered in the idle gate registers, B in second quads, LDS reads + LDS-DMA between MFMAs, no stagger) on top of fp6 loop + la
# baseline (speedup 1.0000x reference)
.LBB0_729:
	s_add_u32 s29, s92, 0xf000000
	s_addc_u32 s30, s93, 0
	s_add_u32 s31, s92, 0x3000000
	s_addc_u32 s33, s93, 0
	s_ashr_i32 s2, s4, 3
	s_add_i32 s2, s7, s2
	s_ashr_i32 s3, s2, 31
	s_lshr_b32 s3, s3, 24
	s_add_i32 s3, s2, s3
	s_ashr_i32 s4, s3, 8
	s_and_b32 s3, s3, 0xffffff00
	s_sub_i32 s2, s2, s3
	s_sext_i32_i16 s3, s2
	s_bfe_u32 s3, s3, 0x3001c
	s_add_i32 s3, s2, s3
	s_lshl_b32 s7, s4, 3
	s_sext_i32_i16 s4, s3
	s_and_b32 s3, s3, 0xfff8
	s_sub_i32 s2, s2, s3
	s_sext_i32_i16 s2, s2
	s_lshr_b32 s4, s4, 3
	s_add_i32 s18, s7, s2
	s_lshr_b32 s6, s5, 6
	s_ashr_i32 s19, s18, 31
	s_bfe_i64 s[10:11], s[4:5], 0x100000
	s_lshr_b32 s8, s5, 8
	s_lshl_b32 s34, s6, 10
	s_lshl_b64 s[2:3], s[18:19], 21
	s_lshl_b64 s[10:11], s[10:11], 20
	v_lshlrev_b32_e32 v1, 4, v0
	s_add_u32 s20, s31, s10
	v_and_b32_e32 v3, 0x3f0, v1
	s_addc_u32 s21, s33, s11
	s_add_i32 s35, s34, 0
	v_or_b32_e32 v102, s34, v3
	s_add_i32 m0, s35, 0x10000
	v_add_u32_e32 v104, 0x2000, v102
	global_load_lds_dwordx4 v102, s[20:21]
	s_add_i32 m0, s35, 0x12000
	s_add_u32 s16, s29, s2
	s_addc_u32 s17, s30, s3
	s_add_i32 s36, s35, 0x2000
	global_load_lds_dwordx4 v104, s[20:21]
	s_mov_b32 m0, s35
	s_add_u32 s2, s16, 0x100000
	global_load_lds_dwordx4 v102, s[16:17]
	s_mov_b32 m0, s36
	s_addc_u32 s3, s17, 0
	s_add_i32 s37, s35, 0x4000
	global_load_lds_dwordx4 v104, s[16:17]
	s_mov_b32 m0, s37
	s_add_i32 s38, s35, 0x6000
	global_load_lds_dwordx4 v102, s[2:3]
	s_mov_b32 m0, s38
	v_mov_b32_e32 v2, 0
	global_load_lds_dwordx4 v104, s[2:3]
	s_cmp_eq_u32 s8, 1
	s_mov_b32 s39, 0
	v_mov_b32_e32 v103, v2
	s_cselect_b64 s[2:3], -1, 0
	s_cmp_lg_u32 s8, 1
	v_mov_b32_e32 v105, v2
	s_cbranch_scc1 .LBB0_731
	s_nop 0
.LBB0_731:
	s_add_u32 s40, s92, 0x13000000
	s_addc_u32 s41, s93, 0
	s_and_b32 s6, s6, 3
	s_lshl_b32 s42, s8, 6
	s_lshl_b32 s9, s8, 13
	s_lshl_b32 s43, s6, 5
	s_lshl_b32 s10, s6, 12
	s_add_u32 s6, s20, 0x4000
	s_addc_u32 s7, s21, 0
	s_add_i32 m0, s35, 0x18000
	v_lshl_add_u64 v[4:5], s[6:7], 0, v[102:103]
	s_waitcnt vmcnt(2)
	s_barrier
	global_load_lds_dwordx4 v[4:5], off
	s_add_i32 m0, s35, 0x1a000
	v_lshl_add_u64 v[4:5], s[6:7], 0, v[104:105]
	s_add_u32 s6, s16, 0x4000
	s_addc_u32 s7, s17, 0
	s_add_i32 s44, s35, 0x8000
	global_load_lds_dwordx4 v[4:5], off
	v_lshl_add_u64 v[4:5], s[6:7], 0, v[102:103]
	s_mov_b32 m0, s44
	s_add_i32 s45, s35, 0xa000
	global_load_lds_dwordx4 v[4:5], off
	v_lshl_add_u64 v[4:5], s[6:7], 0, v[104:105]
	s_mov_b32 m0, s45
	s_cmpk_lt_u32 s5, 0x100
	global_load_lds_dwordx4 v[4:5], off
	s_sext_i32_i16 s19, s4
	v_and_b32_e32 v1, 15, v0
	v_and_b32_e32 v184, 48, v0
	s_cselect_b64 s[6:7], -1, 0
	s_lshl_b32 s4, s8, 3
	v_lshl_or_b32 v4, v1, 6, v184
	v_and_b32_e32 v5, 32, v179
	s_bfe_u32 s47, s5, 0x10006
	s_and_b32 s4, s4, 8
	v_bitop3_b32 v6, v4, s9, v5 bitop3:0xde
	v_lshlrev_b32_e32 v4, 6, v0
	s_movk_i32 s46, 0x3c0
	s_or_b32 s4, s4, s47
	v_and_or_b32 v4, v4, s46, v184
	s_lshl_b32 s48, s4, 10
	v_readlane_b32 s4, v249, 34
	v_bitop3_b32 v185, s10, v4, v5 bitop3:0xf6
	v_mul_u32_u24_e32 v4, 0xcc00, v1
	v_readlane_b32 s5, v249, 35
	s_waitcnt vmcnt(4)
	v_or_b32_e32 v186, v4, v184
	s_ashr_i32 s49, s4, 31
	v_add_u32_e32 v4, s34, v3
	v_mov_b32_e32 v5, v2
	s_mov_b64 s[4:5], 0x10c000
	v_lshl_add_u64 v[106:107], v[4:5], 0, s[4:5]
	v_add_u32_e32 v4, 0x2000, v4
	s_add_i32 s51, 0, 0x10000
	v_lshl_add_u64 v[108:109], v[4:5], 0, s[4:5]
	v_mov_b64_e32 v[110:111], 0x400
	v_mov_b64_e32 v[112:113], 0x3ff
	s_lshl_b32 s50, s43, 1
	v_add_u32_e32 v187, s51, v185
	v_add_u32_e32 v188, 0, v6
	s_barrier
	s_mov_b32 s32, 1
	s_branch .LBB0_734

.LBB0_740:
	s_ashr_i32 s11, s10, 31
	s_lshl_b64 s[12:13], s[10:11], 21
	s_add_u32 s12, s29, s12
	s_addc_u32 s13, s30, s13
	s_and_b64 s[14:15], s[4:5], exec
	s_cselect_b32 s11, s13, s17
	s_cselect_b32 s52, s12, s16
	s_ashr_i32 s9, s8, 31
	s_lshl_b64 s[14:15], s[8:9], 20
	s_add_u32 s14, s31, s14
	s_addc_u32 s15, s33, s15
	s_and_b64 s[22:23], s[4:5], exec
	s_cselect_b32 s53, s15, s21
	s_cselect_b32 s54, s14, s20
	s_lshl_b32 s9, s18, 8
	s_add_i32 s9, s9, s42
	s_mul_i32 s22, s9, 0xcc00
	s_mul_hi_i32 s18, s9, 0xcc00
	s_add_u32 s24, s92, s22
	s_addc_u32 s25, s93, s18
	s_lshl_b32 s18, s19, 7
	s_ashr_i32 s19, s18, 31
	s_lshl_b64 s[22:23], s[18:19], 1
	s_add_u32 s19, s24, s22
	s_addc_u32 s22, s25, s23
	s_add_u32 s19, s19, s50
	s_addc_u32 s22, s22, 0
	s_add_u32 s19, s19, 0x3a004a00
	s_addc_u32 s55, s22, 0
	v_mov_b32_e32 v38, 0
	v_mov_b32_e32 v39, 0
	v_mov_b32_e32 v40, 0
	v_mov_b32_e32 v41, 0
	v_mov_b32_e32 v42, 0
	v_mov_b32_e32 v43, 0
	v_mov_b32_e32 v44, 0
	v_mov_b32_e32 v45, 0
	v_mov_b32_e32 v46, 0
	v_mov_b32_e32 v47, 0
	v_mov_b32_e32 v48, 0
	v_mov_b32_e32 v49, 0
	v_mov_b32_e32 v50, 0
	v_mov_b32_e32 v51, 0
	v_mov_b32_e32 v52, 0
	v_mov_b32_e32 v53, 0
	v_mov_b32_e32 v54, 0
	v_mov_b32_e32 v55, 0
	v_mov_b32_e32 v56, 0
	v_mov_b32_e32 v57, 0
	v_mov_b32_e32 v58, 0
	v_mov_b32_e32 v59, 0
	v_mov_b32_e32 v60, 0
	v_mov_b32_e32 v61, 0
	v_mov_b32_e32 v62, 0
	v_mov_b32_e32 v63, 0
	v_mov_b32_e32 v64, 0
	v_mov_b32_e32 v65, 0
	v_mov_b32_e32 v66, 0
	v_mov_b32_e32 v67, 0
	v_mov_b32_e32 v68, 0
	v_mov_b32_e32 v69, 0
	v_mov_b32_e32 v70, 0
	v_mov_b32_e32 v71, 0
	v_mov_b32_e32 v72, 0
	v_mov_b32_e32 v73, 0
	v_mov_b32_e32 v74, 0
	v_mov_b32_e32 v75, 0
	v_mov_b32_e32 v76, 0
	v_mov_b32_e32 v77, 0
	v_mov_b32_e32 v78, 0
	v_mov_b32_e32 v79, 0
	v_mov_b32_e32 v80, 0
	v_mov_b32_e32 v81, 0
	v_mov_b32_e32 v82, 0
	v_mov_b32_e32 v83, 0
	v_mov_b32_e32 v84, 0
	v_mov_b32_e32 v85, 0
	v_mov_b32_e32 v86, 0
	v_mov_b32_e32 v87, 0
	v_mov_b32_e32 v88, 0
	v_mov_b32_e32 v89, 0
	v_mov_b32_e32 v90, 0
	v_mov_b32_e32 v91, 0
	v_mov_b32_e32 v92, 0
	v_mov_b32_e32 v93, 0
	v_mov_b32_e32 v94, 0
	v_mov_b32_e32 v95, 0
	v_mov_b32_e32 v96, 0
	v_mov_b32_e32 v97, 0
	v_mov_b32_e32 v98, 0
	v_mov_b32_e32 v99, 0
	v_mov_b32_e32 v100, 0
	v_mov_b32_e32 v101, 0
	v_mov_b32_e32 v114, 0
	v_mov_b32_e32 v115, 0
	v_mov_b32_e32 v116, 0
	v_mov_b32_e32 v117, 0
	v_mov_b32_e32 v118, 0
	v_mov_b32_e32 v119, 0
	v_mov_b32_e32 v120, 0
	v_mov_b32_e32 v121, 0
	v_mov_b32_e32 v122, 0
	v_mov_b32_e32 v123, 0
	v_mov_b32_e32 v124, 0
	v_mov_b32_e32 v125, 0
	v_mov_b32_e32 v126, 0
	v_mov_b32_e32 v127, 0
	v_mov_b32_e32 v128, 0
	v_mov_b32_e32 v129, 0
	v_mov_b32_e32 v130, 0
	v_mov_b32_e32 v131, 0
	v_mov_b32_e32 v132, 0
	v_mov_b32_e32 v133, 0
	v_mov_b32_e32 v134, 0
	v_mov_b32_e32 v135, 0
	v_mov_b32_e32 v136, 0
	v_mov_b32_e32 v137, 0
	v_mov_b32_e32 v138, 0
	v_mov_b32_e32 v139, 0
	v_mov_b32_e32 v140, 0
	v_mov_b32_e32 v141, 0
	v_mov_b32_e32 v142, 0
	v_mov_b32_e32 v143, 0
	v_mov_b32_e32 v144, 0
	v_mov_b32_e32 v145, 0
	v_mov_b32_e32 v146, 0
	v_mov_b32_e32 v147, 0
	v_mov_b32_e32 v148, 0
	v_mov_b32_e32 v149, 0
	v_mov_b32_e32 v150, 0
	v_mov_b32_e32 v151, 0
	v_mov_b32_e32 v152, 0
	v_mov_b32_e32 v153, 0
	v_mov_b32_e32 v154, 0
	v_mov_b32_e32 v155, 0
	v_mov_b32_e32 v156, 0
	v_mov_b32_e32 v157, 0
	v_mov_b32_e32 v158, 0
	v_mov_b32_e32 v159, 0
	v_mov_b32_e32 v164, 0
	v_mov_b32_e32 v165, 0
	v_mov_b32_e32 v166, 0
	v_mov_b32_e32 v167, 0
	v_mov_b32_e32 v168, 0
	v_mov_b32_e32 v169, 0
	v_mov_b32_e32 v170, 0
	v_mov_b32_e32 v171, 0
	v_mov_b32_e32 v172, 0
	v_mov_b32_e32 v173, 0
	v_mov_b32_e32 v174, 0
	v_mov_b32_e32 v175, 0
	v_mov_b32_e32 v176, 0
	v_mov_b32_e32 v177, 0
	v_mov_b32_e32 v180, 0
	v_mov_b32_e32 v181, 0
	v_mov_b32_e32 v182, 0
	v_mov_b32_e32 v183, 0
	s_add_u32 s60, s16, 0x8000
	s_addc_u32 s61, s17, 0
	s_add_u32 s62, s20, 0x8000
	s_addc_u32 s63, s21, 0
	s_mov_b32 s58, 0
	s_cmp_eq_u32 s32, 0
	s_cbranch_scc1 .Lg16_rd_g0
	s_add_u32 s26, s16, 0x104000
	s_addc_u32 s27, s17, 0
	s_add_i32 m0, s35, 0xc000
	s_nop 0
	global_load_lds_dwordx4 v102, s[26:27]
	s_add_i32 m0, s35, 0xe000
	s_nop 0
	global_load_lds_dwordx4 v104, s[26:27]
	s_mov_b32 s32, 0
.Lg16_rd_g0:
	ds_read_b128 v[216:219], v188
	ds_read_b128 v[220:223], v188 offset:1024
	ds_read_b128 v[224:227], v188 offset:2048
	ds_read_b128 v[228:231], v188 offset:3072
	ds_read_b128 v[232:235], v188 offset:4096
	ds_read_b128 v[236:239], v188 offset:5120
	ds_read_b128 v[240:243], v188 offset:6144
	ds_read_b128 v[244:247], v188 offset:7168
	ds_read_b128 v[200:203], v187
	ds_read_b128 v[204:207], v187 offset:1024
	ds_read_b128 v[208:211], v187 offset:2048
	ds_read_b128 v[212:215], v187 offset:3072
	s_waitcnt lgkmcnt(0)
	s_barrier
.Lg16_top_g0:
	s_and_b32 s64, s58, 7
	s_cmp_eq_u32 s64, 7
	s_cbranch_scc1 .Lg16_pf_g0
	s_cmp_lg_u32 s64, 0
	s_cbranch_scc1 .Lg16_n_g0
	s_cmp_eq_u32 s58, 0
	s_cbranch_scc1 .Lg16_n_g0
	s_nop 7
	v_lshlrev_b32_e32 v4, 16, v6
	v_and_b32_e32 v5, 0xffff0000, v6
	v_pk_fma_f32 v[182:183], v[98:99], v[4:5], v[182:183]
	v_lshlrev_b32_e32 v4, 16, v8
	v_and_b32_e32 v5, 0xffff0000, v8
	v_pk_fma_f32 v[180:181], v[94:95], v[4:5], v[180:181]
	v_lshlrev_b32_e32 v4, 16, v7
	v_and_b32_e32 v5, 0xffff0000, v7
	v_pk_fma_f32 v[176:177], v[100:101], v[4:5], v[176:177]
	v_lshlrev_b32_e32 v4, 16, v9
	v_and_b32_e32 v5, 0xffff0000, v9
	v_pk_fma_f32 v[174:175], v[96:97], v[4:5], v[174:175]
	v_lshlrev_b32_e32 v4, 16, v10
	v_and_b32_e32 v5, 0xffff0000, v10
	v_pk_fma_f32 v[172:173], v[90:91], v[4:5], v[172:173]
	v_lshlrev_b32_e32 v4, 16, v12
	v_and_b32_e32 v5, 0xffff0000, v12
	v_pk_fma_f32 v[170:171], v[86:87], v[4:5], v[170:171]
	v_lshlrev_b32_e32 v4, 16, v11
	v_and_b32_e32 v5, 0xffff0000, v11
	v_pk_fma_f32 v[168:169], v[92:93], v[4:5], v[168:169]
	v_lshlrev_b32_e32 v4, 16, v13
	v_and_b32_e32 v5, 0xffff0000, v13
	v_pk_fma_f32 v[166:167], v[88:89], v[4:5], v[166:167]
	v_lshlrev_b32_e32 v4, 16, v14
	v_and_b32_e32 v5, 0xffff0000, v14
	v_pk_fma_f32 v[164:165], v[82:83], v[4:5], v[164:165]
	v_lshlrev_b32_e32 v4, 16, v16
	v_and_b32_e32 v5, 0xffff0000, v16
	v_pk_fma_f32 v[158:159], v[78:79], v[4:5], v[158:159]
	v_lshlrev_b32_e32 v4, 16, v15
	v_and_b32_e32 v5, 0xffff0000, v15
	v_pk_fma_f32 v[156:157], v[84:85], v[4:5], v[156:157]
	v_lshlrev_b32_e32 v4, 16, v17
	v_and_b32_e32 v5, 0xffff0000, v17
	v_pk_fma_f32 v[154:155], v[80:81], v[4:5], v[154:155]
	v_lshlrev_b32_e32 v4, 16, v18
	v_and_b32_e32 v5, 0xffff0000, v18
	v_pk_fma_f32 v[152:153], v[74:75], v[4:5], v[152:153]
	v_lshlrev_b32_e32 v4, 16, v20
	v_and_b32_e32 v5, 0xffff0000, v20
	v_pk_fma_f32 v[150:151], v[70:71], v[4:5], v[150:151]
	v_lshlrev_b32_e32 v4, 16, v19
	v_and_b32_e32 v5, 0xffff0000, v19
	v_pk_fma_f32 v[148:149], v[76:77], v[4:5], v[148:149]
	v_lshlrev_b32_e32 v4, 16, v21
	v_and_b32_e32 v5, 0xffff0000, v21
	v_pk_fma_f32 v[146:147], v[72:73], v[4:5], v[146:147]
	v_lshlrev_b32_e32 v4, 16, v22
	v_and_b32_e32 v5, 0xffff0000, v22
	v_pk_fma_f32 v[144:145], v[66:67], v[4:5], v[144:145]
	v_lshlrev_b32_e32 v4, 16, v24
	v_and_b32_e32 v5, 0xffff0000, v24
	v_pk_fma_f32 v[142:143], v[62:63], v[4:5], v[142:143]
	v_lshlrev_b32_e32 v4, 16, v23
	v_and_b32_e32 v5, 0xffff0000, v23
	v_pk_fma_f32 v[140:141], v[68:69], v[4:5], v[140:141]
	v_lshlrev_b32_e32 v4, 16, v25
	v_and_b32_e32 v5, 0xffff0000, v25
	v_pk_fma_f32 v[138:139], v[64:65], v[4:5], v[138:139]
	v_lshlrev_b32_e32 v4, 16, v26
	v_and_b32_e32 v5, 0xffff0000, v26
	v_pk_fma_f32 v[136:137], v[58:59], v[4:5], v[136:137]
	v_lshlrev_b32_e32 v4, 16, v28
	v_and_b32_e32 v5, 0xffff0000, v28
	v_pk_fma_f32 v[134:135], v[54:55], v[4:5], v[134:135]
	v_lshlrev_b32_e32 v4, 16, v27
	v_and_b32_e32 v5, 0xffff0000, v27
	v_pk_fma_f32 v[132:133], v[60:61], v[4:5], v[132:133]
	v_lshlrev_b32_e32 v4, 16, v29
	v_and_b32_e32 v5, 0xffff0000, v29
	v_pk_fma_f32 v[130:131], v[56:57], v[4:5], v[130:131]
	v_lshlrev_b32_e32 v4, 16, v30
	v_and_b32_e32 v5, 0xffff0000, v30
	v_pk_fma_f32 v[128:129], v[50:51], v[4:5], v[128:129]
	v_lshlrev_b32_e32 v4, 16, v32
	v_and_b32_e32 v5, 0xffff0000, v32
	v_pk_fma_f32 v[126:127], v[46:47], v[4:5], v[126:127]
	v_lshlrev_b32_e32 v4, 16, v31
	v_and_b32_e32 v5, 0xffff0000, v31
	v_pk_fma_f32 v[124:125], v[52:53], v[4:5], v[124:125]
	v_lshlrev_b32_e32 v4, 16, v33
	v_and_b32_e32 v5, 0xffff0000, v33
	v_pk_fma_f32 v[122:123], v[48:49], v[4:5], v[122:123]
	v_lshlrev_b32_e32 v4, 16, v34
	v_and_b32_e32 v5, 0xffff0000, v34
	v_pk_fma_f32 v[120:121], v[42:43], v[4:5], v[120:121]
	v_lshlrev_b32_e32 v4, 16, v36
	v_and_b32_e32 v5, 0xffff0000, v36
	v_pk_fma_f32 v[114:115], v[38:39], v[4:5], v[114:115]
	v_lshlrev_b32_e32 v4, 16, v35
	v_and_b32_e32 v5, 0xffff0000, v35
	v_pk_fma_f32 v[118:119], v[44:45], v[4:5], v[118:119]
	v_lshlrev_b32_e32 v4, 16, v37
	v_and_b32_e32 v5, 0xffff0000, v37
	v_pk_fma_f32 v[116:117], v[40:41], v[4:5], v[116:117]
	v_mov_b32_e32 v38, 0
	v_mov_b32_e32 v39, 0
	v_mov_b32_e32 v40, 0
	v_mov_b32_e32 v41, 0
	v_mov_b32_e32 v42, 0
	v_mov_b32_e32 v43, 0
	v_mov_b32_e32 v44, 0
	v_mov_b32_e32 v45, 0
	v_mov_b32_e32 v46, 0
	v_mov_b32_e32 v47, 0
	v_mov_b32_e32 v48, 0
	v_mov_b32_e32 v49, 0
	v_mov_b32_e32 v50, 0
	v_mov_b32_e32 v51, 0
	v_mov_b32_e32 v52, 0
	v_mov_b32_e32 v53, 0
	v_mov_b32_e32 v54, 0
	v_mov_b32_e32 v55, 0
	v_mov_b32_e32 v56, 0
	v_mov_b32_e32 v57, 0
	v_mov_b32_e32 v58, 0
	v_mov_b32_e32 v59, 0
	v_mov_b32_e32 v60, 0
	v_mov_b32_e32 v61, 0
	v_mov_b32_e32 v62, 0
	v_mov_b32_e32 v63, 0
	v_mov_b32_e32 v64, 0
	v_mov_b32_e32 v65, 0
	v_mov_b32_e32 v66, 0
	v_mov_b32_e32 v67, 0
	v_mov_b32_e32 v68, 0
	v_mov_b32_e32 v69, 0
	v_mov_b32_e32 v70, 0
	v_mov_b32_e32 v71, 0
	v_mov_b32_e32 v72, 0
	v_mov_b32_e32 v73, 0
	v_mov_b32_e32 v74, 0
	v_mov_b32_e32 v75, 0
	v_mov_b32_e32 v76, 0
	v_mov_b32_e32 v77, 0
	v_mov_b32_e32 v78, 0
	v_mov_b32_e32 v79, 0
	v_mov_b32_e32 v80, 0
	v_mov_b32_e32 v81, 0
	v_mov_b32_e32 v82, 0
	v_mov_b32_e32 v83, 0
	v_mov_b32_e32 v84, 0
	v_mov_b32_e32 v85, 0
	v_mov_b32_e32 v86, 0
	v_mov_b32_e32 v87, 0
	v_mov_b32_e32 v88, 0
	v_mov_b32_e32 v89, 0
	v_mov_b32_e32 v90, 0
	v_mov_b32_e32 v91, 0
	v_mov_b32_e32 v92, 0
	v_mov_b32_e32 v93, 0
	v_mov_b32_e32 v94, 0
	v_mov_b32_e32 v95, 0
	v_mov_b32_e32 v96, 0
	v_mov_b32_e32 v97, 0
	v_mov_b32_e32 v98, 0
	v_mov_b32_e32 v99, 0
	v_mov_b32_e32 v100, 0
	v_mov_b32_e32 v101, 0
	s_branch .Lg16_n_g0
.Lg16_pf_g0:
	s_lshr_b32 s64, s58, 3
	s_lshl_b32 s64, s64, 13
	s_add_u32 s24, s19, s64
	s_addc_u32 s25, s55, 0
	global_load_dwordx4 v[6:9], v186, s[24:25]
	s_add_u32 s26, s24, 0xcc000
	s_addc_u32 s27, s25, 0
	global_load_dwordx4 v[10:13], v186, s[26:27]
	s_add_u32 s26, s24, 0x198000
	s_addc_u32 s27, s25, 0
	global_load_dwordx4 v[14:17], v186, s[26:27]
	s_add_u32 s26, s24, 0x264000
	s_addc_u32 s27, s25, 0
	global_load_dwordx4 v[18:21], v186, s[26:27]
	s_add_u32 s26, s24, 0x660000
	s_addc_u32 s27, s25, 0
	global_load_dwordx4 v[22:25], v186, s[26:27]
	s_add_u32 s26, s24, 0x72c000
	s_addc_u32 s27, s25, 0
	global_load_dwordx4 v[26:29], v186, s[26:27]
	s_add_u32 s26, s24, 0x7f8000
	s_addc_u32 s27, s25, 0
	global_load_dwordx4 v[30:33], v186, s[26:27]
	s_add_u32 s24, s24, 0x8c4000
	s_addc_u32 s25, s25, 0
	global_load_dwordx4 v[34:37], v186, s[24:25]
.Lg16_p_g0:
	s_cmp_eq_u32 s58, 31
	s_cselect_b32 s22, s52, s60
	s_cselect_b32 s23, s11, s61
	s_cselect_b32 s24, s54, s62
	s_cselect_b32 s25, s53, s63
	s_add_i32 m0, s35, 0x0
	v_mfma_f32_16x16x32_bf16 v[98:101], v[200:203], v[216:219], v[98:101]
	global_load_lds_dwordx4 v102, s[22:23]
	s_add_i32 m0, s35, 0x2000
	v_mfma_f32_16x16x32_bf16 v[98:101], v[204:207], v[220:223], v[98:101]
	global_load_lds_dwordx4 v104, s[22:23]
	s_add_i32 m0, s35, 0x10000
	v_mfma_f32_16x16x32_bf16 v[94:97], v[208:211], v[216:219], v[94:97]
	global_load_lds_dwordx4 v102, s[24:25]
	s_add_i32 m0, s35, 0x12000
	v_mfma_f32_16x16x32_bf16 v[94:97], v[212:215], v[220:223], v[94:97]
	global_load_lds_dwordx4 v104, s[24:25]
	ds_read_b128 v[216:219], v188 offset:16384
	ds_read_b128 v[220:223], v188 offset:17408
	v_mfma_f32_16x16x32_bf16 v[90:93], v[200:203], v[224:227], v[90:93]
	v_mfma_f32_16x16x32_bf16 v[90:93], v[204:207], v[228:231], v[90:93]
	v_mfma_f32_16x16x32_bf16 v[86:89], v[208:211], v[224:227], v[86:89]
	v_mfma_f32_16x16x32_bf16 v[86:89], v[212:215], v[228:231], v[86:89]
	ds_read_b128 v[224:227], v188 offset:18432
	ds_read_b128 v[228:231], v188 offset:19456
	v_mfma_f32_16x16x32_bf16 v[82:85], v[200:203], v[232:235], v[82:85]
	v_mfma_f32_16x16x32_bf16 v[82:85], v[204:207], v[236:239], v[82:85]
	v_mfma_f32_16x16x32_bf16 v[78:81], v[208:211], v[232:235], v[78:81]
	v_mfma_f32_16x16x32_bf16 v[78:81], v[212:215], v[236:239], v[78:81]
	ds_read_b128 v[232:235], v188 offset:20480
	ds_read_b128 v[236:239], v188 offset:21504
	v_mfma_f32_16x16x32_bf16 v[74:77], v[200:203], v[240:243], v[74:77]
	v_mfma_f32_16x16x32_bf16 v[74:77], v[204:207], v[244:247], v[74:77]
	v_mfma_f32_16x16x32_bf16 v[70:73], v[208:211], v[240:243], v[70:73]
	v_mfma_f32_16x16x32_bf16 v[70:73], v[212:215], v[244:247], v[70:73]
	ds_read_b128 v[240:243], v188 offset:22528
	ds_read_b128 v[244:247], v188 offset:23552
	s_waitcnt vmcnt(14)
	s_waitcnt lgkmcnt(0)
	s_barrier
	s_add_u32 s26, s22, 0x100000
	s_addc_u32 s27, s23, 0
	s_add_i32 m0, s35, 0x4000
	v_mfma_f32_16x16x32_bf16 v[66:69], v[200:203], v[216:219], v[66:69]
	global_load_lds_dwordx4 v102, s[26:27]
	v_mfma_f32_16x16x32_bf16 v[58:61], v[200:203], v[224:227], v[58:61]
	ds_read_b128 v[106:109], v187 offset:33792
	s_add_i32 m0, s35, 0x6000
	v_mfma_f32_16x16x32_bf16 v[50:53], v[200:203], v[232:235], v[50:53]
	global_load_lds_dwordx4 v104, s[26:27]
	v_mfma_f32_16x16x32_bf16 v[42:45], v[200:203], v[240:243], v[42:45]
	ds_read_b128 v[160:163], v187 offset:34816
	ds_read_b128 v[200:203], v187 offset:32768
	v_mfma_f32_16x16x32_bf16 v[66:69], v[204:207], v[220:223], v[66:69]
	ds_read_b128 v[250:253], v187 offset:35840
	v_mfma_f32_16x16x32_bf16 v[62:65], v[208:211], v[216:219], v[62:65]
	v_mfma_f32_16x16x32_bf16 v[62:65], v[212:215], v[220:223], v[62:65]
	ds_read_b128 v[216:219], v188 offset:32768
	ds_read_b128 v[220:223], v188 offset:33792
	v_mfma_f32_16x16x32_bf16 v[58:61], v[204:207], v[228:231], v[58:61]
	v_mfma_f32_16x16x32_bf16 v[54:57], v[208:211], v[224:227], v[54:57]
	v_mfma_f32_16x16x32_bf16 v[54:57], v[212:215], v[228:231], v[54:57]
	ds_read_b128 v[224:227], v188 offset:34816
	ds_read_b128 v[228:231], v188 offset:35840
	v_mfma_f32_16x16x32_bf16 v[50:53], v[204:207], v[236:239], v[50:53]
	v_mfma_f32_16x16x32_bf16 v[46:49], v[208:211], v[232:235], v[46:49]
	v_mfma_f32_16x16x32_bf16 v[46:49], v[212:215], v[236:239], v[46:49]
	ds_read_b128 v[232:235], v188 offset:36864
	ds_read_b128 v[236:239], v188 offset:37888
	v_mfma_f32_16x16x32_bf16 v[42:45], v[204:207], v[244:247], v[42:45]
	v_mfma_f32_16x16x32_bf16 v[38:41], v[208:211], v[240:243], v[38:41]
	v_mfma_f32_16x16x32_bf16 v[38:41], v[212:215], v[244:247], v[38:41]
	ds_read_b128 v[240:243], v188 offset:38912
	ds_read_b128 v[244:247], v188 offset:39936
	s_waitcnt vmcnt(14)
	s_waitcnt lgkmcnt(0)
	s_barrier
	s_add_u32 s22, s22, 0x4000
	s_addc_u32 s23, s23, 0
	s_add_u32 s24, s24, 0x4000
	s_addc_u32 s25, s25, 0
	s_add_i32 m0, s35, 0x8000
	v_mfma_f32_16x16x32_bf16 v[98:101], v[200:203], v[216:219], v[98:101]
	global_load_lds_dwordx4 v102, s[22:23]
	s_add_i32 m0, s35, 0xa000
	v_mfma_f32_16x16x32_bf16 v[98:101], v[106:109], v[220:223], v[98:101]
	global_load_lds_dwordx4 v104, s[22:23]
	s_add_i32 m0, s35, 0x18000
	v_mfma_f32_16x16x32_bf16 v[94:97], v[160:163], v[216:219], v[94:97]
	global_load_lds_dwordx4 v102, s[24:25]
	s_add_i32 m0, s35, 0x1a000
	v_mfma_f32_16x16x32_bf16 v[94:97], v[250:253], v[220:223], v[94:97]
	global_load_lds_dwordx4 v104, s[24:25]
	ds_read_b128 v[216:219], v188 offset:49152
	ds_read_b128 v[220:223], v188 offset:50176
	v_mfma_f32_16x16x32_bf16 v[90:93], v[200:203], v[224:227], v[90:93]
	v_mfma_f32_16x16x32_bf16 v[90:93], v[106:109], v[228:231], v[90:93]
	v_mfma_f32_16x16x32_bf16 v[86:89], v[160:163], v[224:227], v[86:89]
	v_mfma_f32_16x16x32_bf16 v[86:89], v[250:253], v[228:231], v[86:89]
	ds_read_b128 v[224:227], v188 offset:51200
	ds_read_b128 v[228:231], v188 offset:52224
	v_mfma_f32_16x16x32_bf16 v[82:85], v[200:203], v[232:235], v[82:85]
	v_mfma_f32_16x16x32_bf16 v[82:85], v[106:109], v[236:239], v[82:85]
	v_mfma_f32_16x16x32_bf16 v[78:81], v[160:163], v[232:235], v[78:81]
	v_mfma_f32_16x16x32_bf16 v[78:81], v[250:253], v[236:239], v[78:81]
	ds_read_b128 v[232:235], v188 offset:53248
	ds_read_b128 v[236:239], v188 offset:54272
	v_mfma_f32_16x16x32_bf16 v[74:77], v[200:203], v[240:243], v[74:77]
	v_mfma_f32_16x16x32_bf16 v[74:77], v[106:109], v[244:247], v[74:77]
	v_mfma_f32_16x16x32_bf16 v[70:73], v[160:163], v[240:243], v[70:73]
	v_mfma_f32_16x16x32_bf16 v[70:73], v[250:253], v[244:247], v[70:73]
	ds_read_b128 v[240:243], v188 offset:55296
	ds_read_b128 v[244:247], v188 offset:56320
	s_waitcnt vmcnt(6)
	s_waitcnt lgkmcnt(0)
	s_barrier
	s_add_u32 s26, s22, 0x100000
	s_addc_u32 s27, s23, 0
	s_add_i32 m0, s35, 0xc000
	v_mfma_f32_16x16x32_bf16 v[66:69], v[200:203], v[216:219], v[66:69]
	global_load_lds_dwordx4 v102, s[26:27]
	v_mfma_f32_16x16x32_bf16 v[58:61], v[200:203], v[224:227], v[58:61]
	ds_read_b128 v[204:207], v187 offset:1024
	s_add_i32 m0, s35, 0xe000
	v_mfma_f32_16x16x32_bf16 v[50:53], v[200:203], v[232:235], v[50:53]
	global_load_lds_dwordx4 v104, s[26:27]
	v_mfma_f32_16x16x32_bf16 v[42:45], v[200:203], v[240:243], v[42:45]
	ds_read_b128 v[208:211], v187 offset:2048
	ds_read_b128 v[200:203], v187
	v_mfma_f32_16x16x32_bf16 v[66:69], v[106:109], v[220:223], v[66:69]
	ds_read_b128 v[212:215], v187 offset:3072
	v_mfma_f32_16x16x32_bf16 v[62:65], v[160:163], v[216:219], v[62:65]
	v_mfma_f32_16x16x32_bf16 v[62:65], v[250:253], v[220:223], v[62:65]
	ds_read_b128 v[216:219], v188
	ds_read_b128 v[220:223], v188 offset:1024
	v_mfma_f32_16x16x32_bf16 v[58:61], v[106:109], v[228:231], v[58:61]
	v_mfma_f32_16x16x32_bf16 v[54:57], v[160:163], v[224:227], v[54:57]
	v_mfma_f32_16x16x32_bf16 v[54:57], v[250:253], v[228:231], v[54:57]
	ds_read_b128 v[224:227], v188 offset:2048
	ds_read_b128 v[228:231], v188 offset:3072
	v_mfma_f32_16x16x32_bf16 v[50:53], v[106:109], v[236:239], v[50:53]
	v_mfma_f32_16x16x32_bf16 v[46:49], v[160:163], v[232:235], v[46:49]
	v_mfma_f32_16x16x32_bf16 v[46:49], v[250:253], v[236:239], v[46:49]
	ds_read_b128 v[232:235], v188 offset:4096
	ds_read_b128 v[236:239], v188 offset:5120
	v_mfma_f32_16x16x32_bf16 v[42:45], v[106:109], v[244:247], v[42:45]
	v_mfma_f32_16x16x32_bf16 v[38:41], v[160:163], v[240:243], v[38:41]
	v_mfma_f32_16x16x32_bf16 v[38:41], v[250:253], v[244:247], v[38:41]
	ds_read_b128 v[240:243], v188 offset:6144
	ds_read_b128 v[244:247], v188 offset:7168
	s_waitcnt vmcnt(6)
	s_waitcnt lgkmcnt(0)
	s_barrier
	s_branch .Lg16_tail_g0
.Lg16_n_g0:
	s_cmp_eq_u32 s58, 31
	s_cselect_b32 s22, s52, s60
	s_cselect_b32 s23, s11, s61
	s_cselect_b32 s24, s54, s62
	s_cselect_b32 s25, s53, s63
	s_add_i32 m0, s35, 0x0
	v_mfma_f32_16x16x32_bf16 v[98:101], v[200:203], v[216:219], v[98:101]
	global_load_lds_dwordx4 v102, s[22:23]
	v_mfma_f32_16x16x32_bf16 v[98:101], v[204:207], v[220:223], v[98:101]
	ds_read_b128 v[6:9], v188 offset:16384
	s_add_i32 m0, s35, 0x2000
	v_mfma_f32_16x16x32_bf16 v[94:97], v[208:211], v[216:219], v[94:97]
	global_load_lds_dwordx4 v104, s[22:23]
	v_mfma_f32_16x16x32_bf16 v[94:97], v[212:215], v[220:223], v[94:97]
	ds_read_b128 v[10:13], v188 offset:17408
	s_add_i32 m0, s35, 0x10000
	v_mfma_f32_16x16x32_bf16 v[90:93], v[200:203], v[224:227], v[90:93]
	global_load_lds_dwordx4 v102, s[24:25]
	v_mfma_f32_16x16x32_bf16 v[90:93], v[204:207], v[228:231], v[90:93]
	ds_read_b128 v[14:17], v188 offset:18432
	s_add_i32 m0, s35, 0x12000
	v_mfma_f32_16x16x32_bf16 v[86:89], v[208:211], v[224:227], v[86:89]
	global_load_lds_dwordx4 v104, s[24:25]
	v_mfma_f32_16x16x32_bf16 v[86:89], v[212:215], v[228:231], v[86:89]
	ds_read_b128 v[18:21], v188 offset:19456
	v_mfma_f32_16x16x32_bf16 v[82:85], v[200:203], v[232:235], v[82:85]
	ds_read_b128 v[22:25], v188 offset:20480
	v_mfma_f32_16x16x32_bf16 v[82:85], v[204:207], v[236:239], v[82:85]
	ds_read_b128 v[26:29], v188 offset:21504
	v_mfma_f32_16x16x32_bf16 v[78:81], v[208:211], v[232:235], v[78:81]
	ds_read_b128 v[30:33], v188 offset:22528
	v_mfma_f32_16x16x32_bf16 v[78:81], v[212:215], v[236:239], v[78:81]
	ds_read_b128 v[34:37], v188 offset:23552
	v_mfma_f32_16x16x32_bf16 v[74:77], v[200:203], v[240:243], v[74:77]
	v_mfma_f32_16x16x32_bf16 v[74:77], v[204:207], v[244:247], v[74:77]
	v_mfma_f32_16x16x32_bf16 v[70:73], v[208:211], v[240:243], v[70:73]
	v_mfma_f32_16x16x32_bf16 v[70:73], v[212:215], v[244:247], v[70:73]
	s_waitcnt vmcnt(6)
	s_waitcnt lgkmcnt(0)
	s_barrier
	s_add_u32 s26, s22, 0x100000
	s_addc_u32 s27, s23, 0
	s_add_i32 m0, s35, 0x4000
	v_mfma_f32_16x16x32_bf16 v[66:69], v[200:203], v[6:9], v[66:69]
	global_load_lds_dwordx4 v102, s[26:27]
	v_mfma_f32_16x16x32_bf16 v[58:61], v[200:203], v[14:17], v[58:61]
	ds_read_b128 v[106:109], v187 offset:33792
	v_mfma_f32_16x16x32_bf16 v[50:53], v[200:203], v[22:25], v[50:53]
	ds_read_b128 v[160:163], v187 offset:34816
	s_add_i32 m0, s35, 0x6000
	v_mfma_f32_16x16x32_bf16 v[42:45], v[200:203], v[30:33], v[42:45]
	global_load_lds_dwordx4 v104, s[26:27]
	ds_read_b128 v[200:203], v187 offset:32768
	v_mfma_f32_16x16x32_bf16 v[66:69], v[204:207], v[10:13], v[66:69]
	ds_read_b128 v[250:253], v187 offset:35840
	v_mfma_f32_16x16x32_bf16 v[62:65], v[208:211], v[6:9], v[62:65]
	ds_read_b128 v[216:219], v188 offset:32768
	v_mfma_f32_16x16x32_bf16 v[62:65], v[212:215], v[10:13], v[62:65]
	ds_read_b128 v[220:223], v188 offset:33792
	v_mfma_f32_16x16x32_bf16 v[58:61], v[204:207], v[18:21], v[58:61]
	ds_read_b128 v[224:227], v188 offset:34816
	v_mfma_f32_16x16x32_bf16 v[54:57], v[208:211], v[14:17], v[54:57]
	ds_read_b128 v[228:231], v188 offset:35840
	v_mfma_f32_16x16x32_bf16 v[54:57], v[212:215], v[18:21], v[54:57]
	ds_read_b128 v[232:235], v188 offset:36864
	v_mfma_f32_16x16x32_bf16 v[50:53], v[204:207], v[26:29], v[50:53]
	ds_read_b128 v[236:239], v188 offset:37888
	v_mfma_f32_16x16x32_bf16 v[46:49], v[208:211], v[22:25], v[46:49]
	ds_read_b128 v[240:243], v188 offset:38912
	v_mfma_f32_16x16x32_bf16 v[46:49], v[212:215], v[26:29], v[46:49]
	ds_read_b128 v[244:247], v188 offset:39936
	v_mfma_f32_16x16x32_bf16 v[42:45], v[204:207], v[34:37], v[42:45]
	v_mfma_f32_16x16x32_bf16 v[38:41], v[208:211], v[30:33], v[38:41]
	v_mfma_f32_16x16x32_bf16 v[38:41], v[212:215], v[34:37], v[38:41]
	s_waitcnt vmcnt(6)
	s_waitcnt lgkmcnt(0)
	s_barrier
	s_add_u32 s22, s22, 0x4000
	s_addc_u32 s23, s23, 0
	s_add_u32 s24, s24, 0x4000
	s_addc_u32 s25, s25, 0
	s_add_i32 m0, s35, 0x8000
	v_mfma_f32_16x16x32_bf16 v[98:101], v[200:203], v[216:219], v[98:101]
	global_load_lds_dwordx4 v102, s[22:23]
	v_mfma_f32_16x16x32_bf16 v[98:101], v[106:109], v[220:223], v[98:101]
	ds_read_b128 v[6:9], v188 offset:49152
	s_add_i32 m0, s35, 0xa000
	v_mfma_f32_16x16x32_bf16 v[94:97], v[160:163], v[216:219], v[94:97]
	global_load_lds_dwordx4 v104, s[22:23]
	v_mfma_f32_16x16x32_bf16 v[94:97], v[250:253], v[220:223], v[94:97]
	ds_read_b128 v[10:13], v188 offset:50176
	s_add_i32 m0, s35, 0x18000
	v_mfma_f32_16x16x32_bf16 v[90:93], v[200:203], v[224:227], v[90:93]
	global_load_lds_dwordx4 v102, s[24:25]
	v_mfma_f32_16x16x32_bf16 v[90:93], v[106:109], v[228:231], v[90:93]
	ds_read_b128 v[14:17], v188 offset:51200
	s_add_i32 m0, s35, 0x1a000
	v_mfma_f32_16x16x32_bf16 v[86:89], v[160:163], v[224:227], v[86:89]
	global_load_lds_dwordx4 v104, s[24:25]
	v_mfma_f32_16x16x32_bf16 v[86:89], v[250:253], v[228:231], v[86:89]
	ds_read_b128 v[18:21], v188 offset:52224
	v_mfma_f32_16x16x32_bf16 v[82:85], v[200:203], v[232:235], v[82:85]
	ds_read_b128 v[22:25], v188 offset:53248
	v_mfma_f32_16x16x32_bf16 v[82:85], v[106:109], v[236:239], v[82:85]
	ds_read_b128 v[26:29], v188 offset:54272
	v_mfma_f32_16x16x32_bf16 v[78:81], v[160:163], v[232:235], v[78:81]
	ds_read_b128 v[30:33], v188 offset:55296
	v_mfma_f32_16x16x32_bf16 v[78:81], v[250:253], v[236:239], v[78:81]
	ds_read_b128 v[34:37], v188 offset:56320
	v_mfma_f32_16x16x32_bf16 v[74:77], v[200:203], v[240:243], v[74:77]
	v_mfma_f32_16x16x32_bf16 v[74:77], v[106:109], v[244:247], v[74:77]
	v_mfma_f32_16x16x32_bf16 v[70:73], v[160:163], v[240:243], v[70:73]
	v_mfma_f32_16x16x32_bf16 v[70:73], v[250:253], v[244:247], v[70:73]
	s_waitcnt vmcnt(6)
	s_waitcnt lgkmcnt(0)
	s_barrier
	s_add_u32 s26, s22, 0x100000
	s_addc_u32 s27, s23, 0
	s_add_i32 m0, s35, 0xc000
	v_mfma_f32_16x16x32_bf16 v[66:69], v[200:203], v[6:9], v[66:69]
	global_load_lds_dwordx4 v102, s[26:27]
	v_mfma_f32_16x16x32_bf16 v[58:61], v[200:203], v[14:17], v[58:61]
	ds_read_b128 v[204:207], v187 offset:1024
	v_mfma_f32_16x16x32_bf16 v[50:53], v[200:203], v[22:25], v[50:53]
	ds_read_b128 v[208:211], v187 offset:2048
	s_add_i32 m0, s35, 0xe000
	v_mfma_f32_16x16x32_bf16 v[42:45], v[200:203], v[30:33], v[42:45]
	global_load_lds_dwordx4 v104, s[26:27]
	ds_read_b128 v[200:203], v187
	v_mfma_f32_16x16x32_bf16 v[66:69], v[106:109], v[10:13], v[66:69]
	ds_read_b128 v[212:215], v187 offset:3072
	v_mfma_f32_16x16x32_bf16 v[62:65], v[160:163], v[6:9], v[62:65]
	ds_read_b128 v[216:219], v188
	v_mfma_f32_16x16x32_bf16 v[62:65], v[250:253], v[10:13], v[62:65]
	ds_read_b128 v[220:223], v188 offset:1024
	v_mfma_f32_16x16x32_bf16 v[58:61], v[106:109], v[18:21], v[58:61]
	ds_read_b128 v[224:227], v188 offset:2048
	v_mfma_f32_16x16x32_bf16 v[54:57], v[160:163], v[14:17], v[54:57]
	ds_read_b128 v[228:231], v188 offset:3072
	v_mfma_f32_16x16x32_bf16 v[54:57], v[250:253], v[18:21], v[54:57]
	ds_read_b128 v[232:235], v188 offset:4096
	v_mfma_f32_16x16x32_bf16 v[50:53], v[106:109], v[26:29], v[50:53]
	ds_read_b128 v[236:239], v188 offset:5120
	v_mfma_f32_16x16x32_bf16 v[46:49], v[160:163], v[22:25], v[46:49]
	ds_read_b128 v[240:243], v188 offset:6144
	v_mfma_f32_16x16x32_bf16 v[46:49], v[250:253], v[26:29], v[46:49]
	ds_read_b128 v[244:247], v188 offset:7168
	v_mfma_f32_16x16x32_bf16 v[42:45], v[106:109], v[34:37], v[42:45]
	v_mfma_f32_16x16x32_bf16 v[38:41], v[160:163], v[30:33], v[38:41]
	v_mfma_f32_16x16x32_bf16 v[38:41], v[250:253], v[34:37], v[38:41]
	s_waitcnt vmcnt(6)
	s_waitcnt lgkmcnt(0)
	s_barrier
	s_branch .Lg16_tail_g0
.Lg16_tail_g0:
	s_add_i32 s58, s58, 1
	s_add_u32 s60, s60, 0x8000
	s_addc_u32 s61, s61, 0
	s_add_u32 s62, s62, 0x8000
	s_addc_u32 s63, s63, 0
	s_cmp_lt_u32 s58, 32
	s_cbranch_scc1 .Lg16_top_g0
	s_nop 7
	s_nop 7
	s_branch .LBB0_746
.LBB0_746:
	s_and_b64 vcc, exec, s[6:7]
	s_cbranch_vccz .LBB0_748
	s_nop 0
.LBB0_748:
	s_nop 0
	v_lshlrev_b32_e32 v4, 16, v6
	v_and_b32_e32 v5, 0xffff0000, v6
	v_pk_fma_f32 v[4:5], v[98:99], v[4:5], v[182:183]
	v_lshlrev_b32_e32 v98, 16, v8
	v_and_b32_e32 v99, 0xffff0000, v8
	v_pk_fma_f32 v[94:95], v[94:95], v[98:99], v[180:181]
	v_lshlrev_b32_e32 v98, 16, v7
	v_and_b32_e32 v99, 0xffff0000, v7
	v_pk_fma_f32 v[98:99], v[100:101], v[98:99], v[176:177]
	v_lshlrev_b32_e32 v100, 16, v9
	v_and_b32_e32 v101, 0xffff0000, v9
	v_pk_fma_f32 v[96:97], v[96:97], v[100:101], v[174:175]
	v_lshlrev_b32_e32 v100, 16, v10
	v_and_b32_e32 v101, 0xffff0000, v10
	v_pk_fma_f32 v[90:91], v[90:91], v[100:101], v[172:173]
	v_lshlrev_b32_e32 v100, 16, v12
	v_and_b32_e32 v101, 0xffff0000, v12
	v_pk_fma_f32 v[86:87], v[86:87], v[100:101], v[170:171]
	v_lshlrev_b32_e32 v100, 16, v11
	v_and_b32_e32 v101, 0xffff0000, v11
	v_pk_fma_f32 v[92:93], v[92:93], v[100:101], v[168:169]
	v_lshlrev_b32_e32 v100, 16, v13
	v_and_b32_e32 v101, 0xffff0000, v13
	v_pk_fma_f32 v[88:89], v[88:89], v[100:101], v[166:167]
	v_lshlrev_b32_e32 v100, 16, v14
	v_and_b32_e32 v101, 0xffff0000, v14
	v_pk_fma_f32 v[82:83], v[82:83], v[100:101], v[164:165]
	v_lshlrev_b32_e32 v100, 16, v16
	v_and_b32_e32 v101, 0xffff0000, v16
	v_pk_fma_f32 v[78:79], v[78:79], v[100:101], v[158:159]
	v_lshlrev_b32_e32 v100, 16, v15
	v_and_b32_e32 v101, 0xffff0000, v15
	v_pk_fma_f32 v[84:85], v[84:85], v[100:101], v[156:157]
	v_lshlrev_b32_e32 v100, 16, v17
	v_and_b32_e32 v101, 0xffff0000, v17
	v_pk_fma_f32 v[80:81], v[80:81], v[100:101], v[154:155]
	v_lshlrev_b32_e32 v100, 16, v18
	v_and_b32_e32 v101, 0xffff0000, v18
	v_pk_fma_f32 v[74:75], v[74:75], v[100:101], v[152:153]
	v_lshlrev_b32_e32 v100, 16, v20
	v_and_b32_e32 v101, 0xffff0000, v20
	v_pk_fma_f32 v[70:71], v[70:71], v[100:101], v[150:151]
	v_lshlrev_b32_e32 v100, 16, v19
	v_and_b32_e32 v101, 0xffff0000, v19
	v_pk_fma_f32 v[76:77], v[76:77], v[100:101], v[148:149]
	v_lshlrev_b32_e32 v100, 16, v21
	v_and_b32_e32 v101, 0xffff0000, v21
	v_pk_fma_f32 v[72:73], v[72:73], v[100:101], v[146:147]
	v_lshlrev_b32_e32 v100, 16, v22
	v_and_b32_e32 v101, 0xffff0000, v22
	v_pk_fma_f32 v[66:67], v[66:67], v[100:101], v[144:145]
	v_lshlrev_b32_e32 v100, 16, v24
	v_and_b32_e32 v101, 0xffff0000, v24
	v_pk_fma_f32 v[62:63], v[62:63], v[100:101], v[142:143]
	v_lshlrev_b32_e32 v100, 16, v23
	v_and_b32_e32 v101, 0xffff0000, v23
	v_pk_fma_f32 v[68:69], v[68:69], v[100:101], v[140:141]
	v_lshlrev_b32_e32 v100, 16, v25
	v_and_b32_e32 v101, 0xffff0000, v25
	v_pk_fma_f32 v[64:65], v[64:65], v[100:101], v[138:139]
	v_lshlrev_b32_e32 v100, 16, v26
	v_and_b32_e32 v101, 0xffff0000, v26
	v_pk_fma_f32 v[58:59], v[58:59], v[100:101], v[136:137]
	v_lshlrev_b32_e32 v100, 16, v28
	v_and_b32_e32 v101, 0xffff0000, v28
	v_pk_fma_f32 v[54:55], v[54:55], v[100:101], v[134:135]
	v_lshlrev_b32_e32 v100, 16, v27
	v_and_b32_e32 v101, 0xffff0000, v27
	v_pk_fma_f32 v[60:61], v[60:61], v[100:101], v[132:133]
	v_lshlrev_b32_e32 v100, 16, v29
	v_and_b32_e32 v101, 0xffff0000, v29
	s_or_b32 s11, s18, s43
	v_pk_fma_f32 v[56:57], v[56:57], v[100:101], v[130:131]
	s_ashr_i32 s16, s11, 6
	v_lshlrev_b32_e32 v100, 16, v30
	v_and_b32_e32 v101, 0xffff0000, v30
	s_ashr_i32 s18, s9, 7
	v_pk_fma_f32 v[50:51], v[50:51], v[100:101], v[128:129]
	v_lshlrev_b32_e32 v100, 16, v32
	v_and_b32_e32 v101, 0xffff0000, v32
	s_ashr_i32 s17, s16, 31
	s_ashr_i32 s19, s18, 31
	v_pk_fma_f32 v[46:47], v[46:47], v[100:101], v[126:127]
	v_lshlrev_b32_e32 v100, 16, v31
	v_and_b32_e32 v101, 0xffff0000, v31
	s_lshl_b64 s[16:17], s[16:17], 14
	s_lshl_b64 s[18:19], s[18:19], 20
	v_pk_fma_f32 v[52:53], v[52:53], v[100:101], v[124:125]
	v_lshlrev_b32_e32 v100, 16, v33
	v_and_b32_e32 v101, 0xffff0000, v33
	s_add_u32 s16, s40, s16
	v_pk_fma_f32 v[48:49], v[48:49], v[100:101], v[122:123]
	s_addc_u32 s17, s41, s17
	v_lshlrev_b32_e32 v100, 16, v34
	v_and_b32_e32 v101, 0xffff0000, v34
	v_pk_fma_f32 v[42:43], v[42:43], v[100:101], v[120:121]
	v_lshlrev_b32_e32 v100, 16, v36
	v_and_b32_e32 v101, 0xffff0000, v36
	s_add_u32 s18, s16, s18
	v_pk_fma_f32 v[100:101], v[38:39], v[100:101], v[114:115]
	v_lshlrev_b32_e32 v38, 16, v35
	v_and_b32_e32 v39, 0xffff0000, v35
	s_addc_u32 s19, s17, s19
	s_or_b32 s11, s9, 16
	v_pk_fma_f32 v[44:45], v[44:45], v[38:39], v[118:119]
	v_lshlrev_b32_e32 v38, 16, v37
	v_and_b32_e32 v39, 0xffff0000, v37
	v_or_b32_e32 v3, s9, v1
	s_lshr_b32 s11, s11, 3
	v_pk_fma_f32 v[114:115], v[40:41], v[38:39], v[116:117]
	v_cvt_pk_bf16_f32 v38, v4, v5
	v_lshlrev_b32_e32 v4, 6, v3
	v_lshlrev_b32_e32 v5, 2, v3
	s_and_b32 s11, s11, 10
	v_and_or_b32 v4, v4, s46, v184
	v_and_b32_e32 v5, 32, v5
	s_or_b32 s11, s11, s47
	v_cvt_pk_bf16_f32 v39, v98, v99
	v_cvt_pk_bf16_f32 v40, v94, v95
	v_cvt_pk_bf16_f32 v41, v96, v97
	v_bitop3_b32 v94, v4, s48, v5 bitop3:0xde
	s_lshl_b32 s11, s11, 10
	global_store_dwordx4 v94, v[38:41], s[18:19]
	s_andn2_b64 vcc, exec, s[4:5]
	s_mov_b64 s[4:5], -1
	v_cvt_pk_bf16_f32 v40, v86, v87
	v_bitop3_b32 v86, v4, s11, v5 bitop3:0xde
	s_or_b32 s11, s9, 32
	s_lshr_b32 s11, s11, 3
	s_or_b32 s9, s9, 48
	s_and_b32 s11, s11, 12
	s_lshr_b32 s9, s9, 3
	s_or_b32 s11, s11, s47
	s_and_b32 s9, s9, 14
	v_cvt_pk_bf16_f32 v38, v90, v91
	v_cvt_pk_bf16_f32 v39, v92, v93
	v_cvt_pk_bf16_f32 v41, v88, v89
	s_lshl_b32 s11, s11, 10
	s_or_b32 s9, s9, s47
	global_store_dwordx4 v86, v[38:41], s[18:19]
	s_lshl_b32 s9, s9, 10
	s_nop 0
	v_cvt_pk_bf16_f32 v38, v82, v83
	v_cvt_pk_bf16_f32 v39, v84, v85
	v_cvt_pk_bf16_f32 v40, v78, v79
	v_cvt_pk_bf16_f32 v41, v80, v81
	v_bitop3_b32 v78, v4, s11, v5 bitop3:0xde
	global_store_dwordx4 v78, v[38:41], s[18:19]
	v_bitop3_b32 v4, v4, s9, v5 bitop3:0xde
	s_nop 0
	v_cvt_pk_bf16_f32 v38, v74, v75
	v_cvt_pk_bf16_f32 v39, v76, v77
	v_cvt_pk_bf16_f32 v40, v70, v71
	v_cvt_pk_bf16_f32 v41, v72, v73
	v_add_u32_e32 v70, 0x80, v3
	global_store_dwordx4 v4, v[38:41], s[18:19]
	v_ashrrev_i32_e32 v4, 7, v70
	v_ashrrev_i32_e32 v5, 31, v4
	v_cvt_pk_bf16_f32 v40, v62, v63
	v_lshlrev_b32_e32 v62, 6, v70
	v_lshlrev_b32_e32 v63, 2, v70
	v_lshlrev_b64 v[4:5], 20, v[4:5]
	v_and_or_b32 v62, v62, s46, v184
	v_and_b32_e32 v63, 32, v63
	v_bitop3_b32 v62, v62, s48, v63 bitop3:0xde
	v_mov_b32_e32 v63, v2
	v_lshl_add_u64 v[4:5], s[16:17], 0, v[4:5]
	v_cvt_pk_bf16_f32 v38, v66, v67
	v_cvt_pk_bf16_f32 v39, v68, v69
	v_cvt_pk_bf16_f32 v41, v64, v65
	v_lshl_add_u64 v[62:63], v[4:5], 0, v[62:63]
	global_store_dwordx4 v[62:63], v[38:41], off
	s_nop 1
	v_cvt_pk_bf16_f32 v40, v54, v55
	v_add_u32_e32 v54, 0x90, v3
	v_lshrrev_b32_e32 v55, 3, v54
	v_cvt_pk_bf16_f32 v41, v56, v57
	v_and_or_b32 v55, v55, 10, s47
	v_lshlrev_b32_e32 v56, 6, v54
	v_lshlrev_b32_e32 v54, 2, v54
	v_and_or_b32 v56, v56, s46, v184
	v_lshlrev_b32_e32 v55, 10, v55
	v_and_b32_e32 v54, 32, v54
	v_bitop3_b32 v54, v56, v55, v54 bitop3:0xde
	v_mov_b32_e32 v55, v2
	v_cvt_pk_bf16_f32 v38, v58, v59
	v_cvt_pk_bf16_f32 v39, v60, v61
	v_lshl_add_u64 v[54:55], v[4:5], 0, v[54:55]
	global_store_dwordx4 v[54:55], v[38:41], off
	s_nop 1
	v_cvt_pk_bf16_f32 v40, v46, v47
	v_add_u32_e32 v46, 0xa0, v3
	v_lshrrev_b32_e32 v47, 3, v46
	v_cvt_pk_bf16_f32 v41, v48, v49
	v_and_or_b32 v47, v47, 12, s47
	v_lshlrev_b32_e32 v48, 6, v46
	v_lshlrev_b32_e32 v46, 2, v46
	v_and_or_b32 v48, v48, s46, v184
	v_lshlrev_b32_e32 v47, 10, v47
	v_and_b32_e32 v46, 32, v46
	v_bitop3_b32 v46, v48, v47, v46 bitop3:0xde
	v_mov_b32_e32 v47, v2
	v_cvt_pk_bf16_f32 v38, v50, v51
	v_cvt_pk_bf16_f32 v39, v52, v53
	v_lshl_add_u64 v[46:47], v[4:5], 0, v[46:47]
	v_add_u32_e32 v3, 0xb0, v3
	global_store_dwordx4 v[46:47], v[38:41], off
	s_nop 1
	v_cvt_pk_bf16_f32 v38, v42, v43
	v_lshrrev_b32_e32 v42, 3, v3
	v_and_or_b32 v42, v42, 14, s47
	v_lshlrev_b32_e32 v43, 6, v3
	v_lshlrev_b32_e32 v3, 2, v3
	v_and_or_b32 v43, v43, s46, v184
	v_lshlrev_b32_e32 v42, 10, v42
	v_and_b32_e32 v3, 32, v3
	v_bitop3_b32 v42, v43, v42, v3 bitop3:0xde
	v_mov_b32_e32 v43, v2
	v_cvt_pk_bf16_f32 v39, v44, v45
	v_cvt_pk_bf16_f32 v40, v100, v101
	v_cvt_pk_bf16_f32 v41, v114, v115
	v_lshl_add_u64 v[4:5], v[4:5], 0, v[42:43]
	global_store_dwordx4 v[4:5], v[38:41], off
	s_cbranch_vccnz .LBB0_733
	s_andn2_b64 vcc, exec, s[2:3]
	s_cbranch_vccnz .LBB0_732
	s_nop 0
	s_branch .LBB0_732

.LBB0_1512:
	s_add_u32 s29, s92, 0xf000000
	s_addc_u32 s30, s93, 0
	s_add_u32 s31, s92, 0x5000000
	s_addc_u32 s33, s93, 0
	s_ashr_i32 s2, s4, 3
	s_add_i32 s2, s7, s2
	s_ashr_i32 s3, s2, 31
	s_lshr_b32 s3, s3, 24
	s_add_i32 s3, s2, s3
	s_ashr_i32 s4, s3, 8
	s_and_b32 s3, s3, 0xffffff00
	s_sub_i32 s2, s2, s3
	s_sext_i32_i16 s3, s2
	s_bfe_u32 s3, s3, 0x3001c
	s_add_i32 s3, s2, s3
	s_lshl_b32 s7, s4, 3
	s_sext_i32_i16 s4, s3
	s_and_b32 s3, s3, 0xfff8
	s_sub_i32 s2, s2, s3
	s_sext_i32_i16 s2, s2
	s_lshr_b32 s4, s4, 3
	s_add_i32 s18, s7, s2
	s_lshr_b32 s6, s5, 6
	s_ashr_i32 s19, s18, 31
	s_bfe_i64 s[10:11], s[4:5], 0x100000
	s_lshr_b32 s8, s5, 8
	s_lshl_b32 s34, s6, 10
	s_lshl_b64 s[2:3], s[18:19], 21
	s_lshl_b64 s[10:11], s[10:11], 20
	v_lshlrev_b32_e32 v1, 4, v0
	s_add_u32 s20, s31, s10
	v_and_b32_e32 v3, 0x3f0, v1
	s_addc_u32 s21, s33, s11
	s_add_i32 s35, s34, 0
	v_or_b32_e32 v102, s34, v3
	s_add_i32 m0, s35, 0x10000
	v_add_u32_e32 v104, 0x2000, v102
	global_load_lds_dwordx4 v102, s[20:21]
	s_add_i32 m0, s35, 0x12000
	s_add_u32 s16, s29, s2
	s_addc_u32 s17, s30, s3
	s_add_i32 s36, s35, 0x2000
	global_load_lds_dwordx4 v104, s[20:21]
	s_mov_b32 m0, s35
	s_add_u32 s2, s16, 0x100000
	global_load_lds_dwordx4 v102, s[16:17]
	s_mov_b32 m0, s36
	s_addc_u32 s3, s17, 0
	s_add_i32 s37, s35, 0x4000
	global_load_lds_dwordx4 v104, s[16:17]
	s_mov_b32 m0, s37
	s_add_i32 s38, s35, 0x6000
	global_load_lds_dwordx4 v102, s[2:3]
	s_mov_b32 m0, s38
	v_mov_b32_e32 v2, 0
	global_load_lds_dwordx4 v104, s[2:3]
	s_cmp_eq_u32 s8, 1
	s_mov_b32 s39, 0
	v_mov_b32_e32 v103, v2
	s_cselect_b64 s[2:3], -1, 0
	s_cmp_lg_u32 s8, 1
	v_mov_b32_e32 v105, v2
	s_cbranch_scc1 .LBB0_1514
	s_nop 0

.Lg16_rd_g1:
	ds_read_b128 v[206:209], v188
	ds_read_b128 v[210:213], v188 offset:1024
	ds_read_b128 v[214:217], v188 offset:2048
	ds_read_b128 v[218:221], v188 offset:3072
	ds_read_b128 v[222:225], v188 offset:4096
	ds_read_b128 v[226:229], v188 offset:5120
	ds_read_b128 v[230:233], v188 offset:6144
	ds_read_b128 v[234:237], v188 offset:7168
	ds_read_b128 v[190:193], v187
	ds_read_b128 v[194:197], v187 offset:1024
	ds_read_b128 v[198:201], v187 offset:2048
	ds_read_b128 v[202:205], v187 offset:3072
	s_waitcnt lgkmcnt(0)
	s_barrier

.Lg16_p_g1:
	s_cmp_eq_u32 s58, 31
	s_cselect_b32 s22, s52, s60
	s_cselect_b32 s23, s11, s61
	s_cselect_b32 s24, s54, s62
	s_cselect_b32 s25, s53, s63
	s_add_i32 m0, s35, 0x0
	v_mfma_f32_16x16x32_bf16 v[98:101], v[190:193], v[206:209], v[98:101]
	global_load_lds_dwordx4 v102, s[22:23]
	s_add_i32 m0, s35, 0x2000
	v_mfma_f32_16x16x32_bf16 v[98:101], v[194:197], v[210:213], v[98:101]
	global_load_lds_dwordx4 v104, s[22:23]
	s_add_i32 m0, s35, 0x10000
	v_mfma_f32_16x16x32_bf16 v[94:97], v[198:201], v[206:209], v[94:97]
	global_load_lds_dwordx4 v102, s[24:25]
	s_add_i32 m0, s35, 0x12000
	v_mfma_f32_16x16x32_bf16 v[94:97], v[202:205], v[210:213], v[94:97]
	global_load_lds_dwordx4 v104, s[24:25]
	ds_read_b128 v[206:209], v188 offset:16384
	ds_read_b128 v[210:213], v188 offset:17408
	v_mfma_f32_16x16x32_bf16 v[90:93], v[190:193], v[214:217], v[90:93]
	v_mfma_f32_16x16x32_bf16 v[90:93], v[194:197], v[218:221], v[90:93]
	v_mfma_f32_16x16x32_bf16 v[86:89], v[198:201], v[214:217], v[86:89]
	v_mfma_f32_16x16x32_bf16 v[86:89], v[202:205], v[218:221], v[86:89]
	ds_read_b128 v[214:217], v188 offset:18432
	ds_read_b128 v[218:221], v188 offset:19456
	v_mfma_f32_16x16x32_bf16 v[82:85], v[190:193], v[222:225], v[82:85]
	v_mfma_f32_16x16x32_bf16 v[82:85], v[194:197], v[226:229], v[82:85]
	v_mfma_f32_16x16x32_bf16 v[78:81], v[198:201], v[222:225], v[78:81]
	v_mfma_f32_16x16x32_bf16 v[78:81], v[202:205], v[226:229], v[78:81]
	ds_read_b128 v[222:225], v188 offset:20480
	ds_read_b128 v[226:229], v188 offset:21504
	v_mfma_f32_16x16x32_bf16 v[74:77], v[190:193], v[230:233], v[74:77]
	v_mfma_f32_16x16x32_bf16 v[74:77], v[194:197], v[234:237], v[74:77]
	v_mfma_f32_16x16x32_bf16 v[70:73], v[198:201], v[230:233], v[70:73]
	v_mfma_f32_16x16x32_bf16 v[70:73], v[202:205], v[234:237], v[70:73]
	ds_read_b128 v[230:233], v188 offset:22528
	ds_read_b128 v[234:237], v188 offset:23552
	s_waitcnt vmcnt(14)
	s_waitcnt lgkmcnt(0)
	s_barrier
	s_add_u32 s26, s22, 0x100000
	s_addc_u32 s27, s23, 0
	s_add_i32 m0, s35, 0x4000
	v_mfma_f32_16x16x32_bf16 v[66:69], v[190:193], v[206:209], v[66:69]
	global_load_lds_dwordx4 v102, s[26:27]
	v_mfma_f32_16x16x32_bf16 v[58:61], v[190:193], v[214:217], v[58:61]
	ds_read_b128 v[106:109], v187 offset:33792
	s_add_i32 m0, s35, 0x6000
	v_mfma_f32_16x16x32_bf16 v[50:53], v[190:193], v[222:225], v[50:53]
	global_load_lds_dwordx4 v104, s[26:27]
	v_mfma_f32_16x16x32_bf16 v[42:45], v[190:193], v[230:233], v[42:45]
	ds_read_b128 v[160:163], v187 offset:34816
	ds_read_b128 v[190:193], v187 offset:32768
	v_mfma_f32_16x16x32_bf16 v[66:69], v[194:197], v[210:213], v[66:69]
	ds_read_b128 v[250:253], v187 offset:35840
	v_mfma_f32_16x16x32_bf16 v[62:65], v[198:201], v[206:209], v[62:65]
	v_mfma_f32_16x16x32_bf16 v[62:65], v[202:205], v[210:213], v[62:65]
	ds_read_b128 v[206:209], v188 offset:32768
	ds_read_b128 v[210:213], v188 offset:33792
	v_mfma_f32_16x16x32_bf16 v[58:61], v[194:197], v[218:221], v[58:61]
	v_mfma_f32_16x16x32_bf16 v[54:57], v[198:201], v[214:217], v[54:57]
	v_mfma_f32_16x16x32_bf16 v[54:57], v[202:205], v[218:221], v[54:57]
	ds_read_b128 v[214:217], v188 offset:34816
	ds_read_b128 v[218:221], v188 offset:35840
	v_mfma_f32_16x16x32_bf16 v[50:53], v[194:197], v[226:229], v[50:53]
	v_mfma_f32_16x16x32_bf16 v[46:49], v[198:201], v[222:225], v[46:49]
	v_mfma_f32_16x16x32_bf16 v[46:49], v[202:205], v[226:229], v[46:49]
	ds_read_b128 v[222:225], v188 offset:36864
	ds_read_b128 v[226:229], v188 offset:37888
	v_mfma_f32_16x16x32_bf16 v[42:45], v[194:197], v[234:237], v[42:45]
	v_mfma_f32_16x16x32_bf16 v[38:41], v[198:201], v[230:233], v[38:41]
	v_mfma_f32_16x16x32_bf16 v[38:41], v[202:205], v[234:237], v[38:41]
	ds_read_b128 v[230:233], v188 offset:38912
	ds_read_b128 v[234:237], v188 offset:39936
	s_waitcnt vmcnt(14)
	s_waitcnt lgkmcnt(0)
	s_barrier
	s_add_u32 s22, s22, 0x4000
	s_addc_u32 s23, s23, 0
	s_add_u32 s24, s24, 0x4000
	s_addc_u32 s25, s25, 0
	s_add_i32 m0, s35, 0x8000
	v_mfma_f32_16x16x32_bf16 v[98:101], v[190:193], v[206:209], v[98:101]
	global_load_lds_dwordx4 v102, s[22:23]
	s_add_i32 m0, s35, 0xa000
	v_mfma_f32_16x16x32_bf16 v[98:101], v[106:109], v[210:213], v[98:101]
	global_load_lds_dwordx4 v104, s[22:23]
	s_add_i32 m0, s35, 0x18000
	v_mfma_f32_16x16x32_bf16 v[94:97], v[160:163], v[206:209], v[94:97]
	global_load_lds_dwordx4 v102, s[24:25]
	s_add_i32 m0, s35, 0x1a000
	v_mfma_f32_16x16x32_bf16 v[94:97], v[250:253], v[210:213], v[94:97]
	global_load_lds_dwordx4 v104, s[24:25]
	ds_read_b128 v[206:209], v188 offset:49152
	ds_read_b128 v[210:213], v188 offset:50176
	v_mfma_f32_16x16x32_bf16 v[90:93], v[190:193], v[214:217], v[90:93]
	v_mfma_f32_16x16x32_bf16 v[90:93], v[106:109], v[218:221], v[90:93]
	v_mfma_f32_16x16x32_bf16 v[86:89], v[160:163], v[214:217], v[86:89]
	v_mfma_f32_16x16x32_bf16 v[86:89], v[250:253], v[218:221], v[86:89]
	ds_read_b128 v[214:217], v188 offset:51200
	ds_read_b128 v[218:221], v188 offset:52224
	v_mfma_f32_16x16x32_bf16 v[82:85], v[190:193], v[222:225], v[82:85]
	v_mfma_f32_16x16x32_bf16 v[82:85], v[106:109], v[226:229], v[82:85]
	v_mfma_f32_16x16x32_bf16 v[78:81], v[160:163], v[222:225], v[78:81]
	v_mfma_f32_16x16x32_bf16 v[78:81], v[250:253], v[226:229], v[78:81]
	ds_read_b128 v[222:225], v188 offset:53248
	ds_read_b128 v[226:229], v188 offset:54272
	v_mfma_f32_16x16x32_bf16 v[74:77], v[190:193], v[230:233], v[74:77]
	v_mfma_f32_16x16x32_bf16 v[74:77], v[106:109], v[234:237], v[74:77]
	v_mfma_f32_16x16x32_bf16 v[70:73], v[160:163], v[230:233], v[70:73]
	v_mfma_f32_16x16x32_bf16 v[70:73], v[250:253], v[234:237], v[70:73]
	ds_read_b128 v[230:233], v188 offset:55296
	ds_read_b128 v[234:237], v188 offset:56320
	s_waitcnt vmcnt(6)
	s_waitcnt lgkmcnt(0)
	s_barrier
	s_add_u32 s26, s22, 0x100000
	s_addc_u32 s27, s23, 0
	s_add_i32 m0, s35, 0xc000
	v_mfma_f32_16x16x32_bf16 v[66:69], v[190:193], v[206:209], v[66:69]
	global_load_lds_dwordx4 v102, s[26:27]
	v_mfma_f32_16x16x32_bf16 v[58:61], v[190:193], v[214:217], v[58:61]
	ds_read_b128 v[194:197], v187 offset:1024
	s_add_i32 m0, s35, 0xe000
	v_mfma_f32_16x16x32_bf16 v[50:53], v[190:193], v[222:225], v[50:53]
	global_load_lds_dwordx4 v104, s[26:27]
	v_mfma_f32_16x16x32_bf16 v[42:45], v[190:193], v[230:233], v[42:45]
	ds_read_b128 v[198:201], v187 offset:2048
	ds_read_b128 v[190:193], v187
	v_mfma_f32_16x16x32_bf16 v[66:69], v[106:109], v[210:213], v[66:69]
	ds_read_b128 v[202:205], v187 offset:3072
	v_mfma_f32_16x16x32_bf16 v[62:65], v[160:163], v[206:209], v[62:65]
	v_mfma_f32_16x16x32_bf16 v[62:65], v[250:253], v[210:213], v[62:65]
	ds_read_b128 v[206:209], v188
	ds_read_b128 v[210:213], v188 offset:1024
	v_mfma_f32_16x16x32_bf16 v[58:61], v[106:109], v[218:221], v[58:61]
	v_mfma_f32_16x16x32_bf16 v[54:57], v[160:163], v[214:217], v[54:57]
	v_mfma_f32_16x16x32_bf16 v[54:57], v[250:253], v[218:221], v[54:57]
	ds_read_b128 v[214:217], v188 offset:2048
	ds_read_b128 v[218:221], v188 offset:3072
	v_mfma_f32_16x16x32_bf16 v[50:53], v[106:109], v[226:229], v[50:53]
	v_mfma_f32_16x16x32_bf16 v[46:49], v[160:163], v[222:225], v[46:49]
	v_mfma_f32_16x16x32_bf16 v[46:49], v[250:253], v[226:229], v[46:49]
	ds_read_b128 v[222:225], v188 offset:4096
	ds_read_b128 v[226:229], v188 offset:5120
	v_mfma_f32_16x16x32_bf16 v[42:45], v[106:109], v[234:237], v[42:45]
	v_mfma_f32_16x16x32_bf16 v[38:41], v[160:163], v[230:233], v[38:41]
	v_mfma_f32_16x16x32_bf16 v[38:41], v[250:253], v[234:237], v[38:41]
	ds_read_b128 v[230:233], v188 offset:6144
	ds_read_b128 v[234:237], v188 offset:7168
	s_waitcnt vmcnt(6)
	s_waitcnt lgkmcnt(0)
	s_barrier
	s_branch .Lg16_tail_g1
.Lg16_n_g1:
	s_cmp_eq_u32 s58, 31
	s_cselect_b32 s22, s52, s60
	s_cselect_b32 s23, s11, s61
	s_cselect_b32 s24, s54, s62
	s_cselect_b32 s25, s53, s63
	s_add_i32 m0, s35, 0x0
	v_mfma_f32_16x16x32_bf16 v[98:101], v[190:193], v[206:209], v[98:101]
	global_load_lds_dwordx4 v102, s[22:23]
	v_mfma_f32_16x16x32_bf16 v[98:101], v[194:197], v[210:213], v[98:101]
	ds_read_b128 v[6:9], v188 offset:16384
	s_add_i32 m0, s35, 0x2000
	v_mfma_f32_16x16x32_bf16 v[94:97], v[198:201], v[206:209], v[94:97]
	global_load_lds_dwordx4 v104, s[22:23]
	v_mfma_f32_16x16x32_bf16 v[94:97], v[202:205], v[210:213], v[94:97]
	ds_read_b128 v[10:13], v188 offset:17408
	s_add_i32 m0, s35, 0x10000
	v_mfma_f32_16x16x32_bf16 v[90:93], v[190:193], v[214:217], v[90:93]
	global_load_lds_dwordx4 v102, s[24:25]
	v_mfma_f32_16x16x32_bf16 v[90:93], v[194:197], v[218:221], v[90:93]
	ds_read_b128 v[14:17], v188 offset:18432
	s_add_i32 m0, s35, 0x12000
	v_mfma_f32_16x16x32_bf16 v[86:89], v[198:201], v[214:217], v[86:89]
	global_load_lds_dwordx4 v104, s[24:25]
	v_mfma_f32_16x16x32_bf16 v[86:89], v[202:205], v[218:221], v[86:89]
	ds_read_b128 v[18:21], v188 offset:19456
	v_mfma_f32_16x16x32_bf16 v[82:85], v[190:193], v[222:225], v[82:85]
	ds_read_b128 v[22:25], v188 offset:20480
	v_mfma_f32_16x16x32_bf16 v[82:85], v[194:197], v[226:229], v[82:85]
	ds_read_b128 v[26:29], v188 offset:21504
	v_mfma_f32_16x16x32_bf16 v[78:81], v[198:201], v[222:225], v[78:81]
	ds_read_b128 v[30:33], v188 offset:22528
	v_mfma_f32_16x16x32_bf16 v[78:81], v[202:205], v[226:229], v[78:81]
	ds_read_b128 v[34:37], v188 offset:23552
	v_mfma_f32_16x16x32_bf16 v[74:77], v[190:193], v[230:233], v[74:77]
	v_mfma_f32_16x16x32_bf16 v[74:77], v[194:197], v[234:237], v[74:77]
	v_mfma_f32_16x16x32_bf16 v[70:73], v[198:201], v[230:233], v[70:73]
	v_mfma_f32_16x16x32_bf16 v[70:73], v[202:205], v[234:237], v[70:73]
	s_waitcnt vmcnt(6)
	s_waitcnt lgkmcnt(0)
	s_barrier
	s_add_u32 s26, s22, 0x100000
	s_addc_u32 s27, s23, 0
	s_add_i32 m0, s35, 0x4000
	v_mfma_f32_16x16x32_bf16 v[66:69], v[190:193], v[6:9], v[66:69]
	global_load_lds_dwordx4 v102, s[26:27]
	v_mfma_f32_16x16x32_bf16 v[58:61], v[190:193], v[14:17], v[58:61]
	ds_read_b128 v[106:109], v187 offset:33792
	v_mfma_f32_16x16x32_bf16 v[50:53], v[190:193], v[22:25], v[50:53]
	ds_read_b128 v[160:163], v187 offset:34816
	s_add_i32 m0, s35, 0x6000
	v_mfma_f32_16x16x32_bf16 v[42:45], v[190:193], v[30:33], v[42:45]
	global_load_lds_dwordx4 v104, s[26:27]
	ds_read_b128 v[190:193], v187 offset:32768
	v_mfma_f32_16x16x32_bf16 v[66:69], v[194:197], v[10:13], v[66:69]
	ds_read_b128 v[250:253], v187 offset:35840
	v_mfma_f32_16x16x32_bf16 v[62:65], v[198:201], v[6:9], v[62:65]
	ds_read_b128 v[206:209], v188 offset:32768
	v_mfma_f32_16x16x32_bf16 v[62:65], v[202:205], v[10:13], v[62:65]
	ds_read_b128 v[210:213], v188 offset:33792
	v_mfma_f32_16x16x32_bf16 v[58:61], v[194:197], v[18:21], v[58:61]
	ds_read_b128 v[214:217], v188 offset:34816
	v_mfma_f32_16x16x32_bf16 v[54:57], v[198:201], v[14:17], v[54:57]
	ds_read_b128 v[218:221], v188 offset:35840
	v_mfma_f32_16x16x32_bf16 v[54:57], v[202:205], v[18:21], v[54:57]
	ds_read_b128 v[222:225], v188 offset:36864
	v_mfma_f32_16x16x32_bf16 v[50:53], v[194:197], v[26:29], v[50:53]
	ds_read_b128 v[226:229], v188 offset:37888
	v_mfma_f32_16x16x32_bf16 v[46:49], v[198:201], v[22:25], v[46:49]
	ds_read_b128 v[230:233], v188 offset:38912
	v_mfma_f32_16x16x32_bf16 v[46:49], v[202:205], v[26:29], v[46:49]
	ds_read_b128 v[234:237], v188 offset:39936
	v_mfma_f32_16x16x32_bf16 v[42:45], v[194:197], v[34:37], v[42:45]
	v_mfma_f32_16x16x32_bf16 v[38:41], v[198:201], v[30:33], v[38:41]
	v_mfma_f32_16x16x32_bf16 v[38:41], v[202:205], v[34:37], v[38:41]
	s_waitcnt vmcnt(6)
	s_waitcnt lgkmcnt(0)
	s_barrier
	s_add_u32 s22, s22, 0x4000
	s_addc_u32 s23, s23, 0
	s_add_u32 s24, s24, 0x4000
	s_addc_u32 s25, s25, 0
	s_add_i32 m0, s35, 0x8000
	v_mfma_f32_16x16x32_bf16 v[98:101], v[190:193], v[206:209], v[98:101]
	global_load_lds_dwordx4 v102, s[22:23]
	v_mfma_f32_16x16x32_bf16 v[98:101], v[106:109], v[210:213], v[98:101]
	ds_read_b128 v[6:9], v188 offset:49152
	s_add_i32 m0, s35, 0xa000
	v_mfma_f32_16x16x32_bf16 v[94:97], v[160:163], v[206:209], v[94:97]
	global_load_lds_dwordx4 v104, s[22:23]
	v_mfma_f32_16x16x32_bf16 v[94:97], v[250:253], v[210:213], v[94:97]
	ds_read_b128 v[10:13], v188 offset:50176
	s_add_i32 m0, s35, 0x18000
	v_mfma_f32_16x16x32_bf16 v[90:93], v[190:193], v[214:217], v[90:93]
	global_load_lds_dwordx4 v102, s[24:25]
	v_mfma_f32_16x16x32_bf16 v[90:93], v[106:109], v[218:221], v[90:93]
	ds_read_b128 v[14:17], v188 offset:51200
	s_add_i32 m0, s35, 0x1a000
	v_mfma_f32_16x16x32_bf16 v[86:89], v[160:163], v[214:217], v[86:89]
	global_load_lds_dwordx4 v104, s[24:25]
	v_mfma_f32_16x16x32_bf16 v[86:89], v[250:253], v[218:221], v[86:89]
	ds_read_b128 v[18:21], v188 offset:52224
	v_mfma_f32_16x16x32_bf16 v[82:85], v[190:193], v[222:225], v[82:85]
	ds_read_b128 v[22:25], v188 offset:53248
	v_mfma_f32_16x16x32_bf16 v[82:85], v[106:109], v[226:229], v[82:85]
	ds_read_b128 v[26:29], v188 offset:54272
	v_mfma_f32_16x16x32_bf16 v[78:81], v[160:163], v[222:225], v[78:81]
	ds_read_b128 v[30:33], v188 offset:55296
	v_mfma_f32_16x16x32_bf16 v[78:81], v[250:253], v[226:229], v[78:81]
	ds_read_b128 v[34:37], v188 offset:56320
	v_mfma_f32_16x16x32_bf16 v[74:77], v[190:193], v[230:233], v[74:77]
	v_mfma_f32_16x16x32_bf16 v[74:77], v[106:109], v[234:237], v[74:77]
	v_mfma_f32_16x16x32_bf16 v[70:73], v[160:163], v[230:233], v[70:73]
	v_mfma_f32_16x16x32_bf16 v[70:73], v[250:253], v[234:237], v[70:73]
	s_waitcnt vmcnt(6)
	s_waitcnt lgkmcnt(0)
	s_barrier
	s_add_u32 s26, s22, 0x100000
	s_addc_u32 s27, s23, 0
	s_add_i32 m0, s35, 0xc000
	v_mfma_f32_16x16x32_bf16 v[66:69], v[190:193], v[6:9], v[66:69]
	global_load_lds_dwordx4 v102, s[26:27]
	v_mfma_f32_16x16x32_bf16 v[58:61], v[190:193], v[14:17], v[58:61]
	ds_read_b128 v[194:197], v187 offset:1024
	v_mfma_f32_16x16x32_bf16 v[50:53], v[190:193], v[22:25], v[50:53]
	ds_read_b128 v[198:201], v187 offset:2048
	s_add_i32 m0, s35, 0xe000
	v_mfma_f32_16x16x32_bf16 v[42:45], v[190:193], v[30:33], v[42:45]
	global_load_lds_dwordx4 v104, s[26:27]
	ds_read_b128 v[190:193], v187
	v_mfma_f32_16x16x32_bf16 v[66:69], v[106:109], v[10:13], v[66:69]
	ds_read_b128 v[202:205], v187 offset:3072
	v_mfma_f32_16x16x32_bf16 v[62:65], v[160:163], v[6:9], v[62:65]
	ds_read_b128 v[206:209], v188
	v_mfma_f32_16x16x32_bf16 v[62:65], v[250:253], v[10:13], v[62:65]
	ds_read_b128 v[210:213], v188 offset:1024
	v_mfma_f32_16x16x32_bf16 v[58:61], v[106:109], v[18:21], v[58:61]
	ds_read_b128 v[214:217], v188 offset:2048
	v_mfma_f32_16x16x32_bf16 v[54:57], v[160:163], v[14:17], v[54:57]
	ds_read_b128 v[218:221], v188 offset:3072
	v_mfma_f32_16x16x32_bf16 v[54:57], v[250:253], v[18:21], v[54:57]
	ds_read_b128 v[222:225], v188 offset:4096
	v_mfma_f32_16x16x32_bf16 v[50:53], v[106:109], v[26:29], v[50:53]
	ds_read_b128 v[226:229], v188 offset:5120
	v_mfma_f32_16x16x32_bf16 v[46:49], v[160:163], v[22:25], v[46:49]
	ds_read_b128 v[230:233], v188 offset:6144
	v_mfma_f32_16x16x32_bf16 v[46:49], v[250:253], v[26:29], v[46:49]
	ds_read_b128 v[234:237], v188 offset:7168
	v_mfma_f32_16x16x32_bf16 v[42:45], v[106:109], v[34:37], v[42:45]
	v_mfma_f32_16x16x32_bf16 v[38:41], v[160:163], v[30:33], v[38:41]
	v_mfma_f32_16x16x32_bf16 v[38:41], v[250:253], v[34:37], v[38:41]
	s_waitcnt vmcnt(6)
	s_waitcnt lgkmcnt(0)
	s_barrier
	s_branch .Lg16_tail_g1
